# thin_rows: second 16-row chunk given to waves of WGs 32-35 (one Q tile) instead of WGs 0-3 (two Q tiles)
# baseline (speedup 1.0000x reference)
; #define TID() tid_now(wv)
; #define BID() opq_s((int)blockIdx.x)
; #define GDIM() opq_s((int)gridDim.x)
; DEVI const float* IN(int i) { return *(const float* const __attribute__((address_space(4)))*)(kargs() + 8 * i); }
; DEVI float* OUTP() { return *(float* const __attribute__((address_space(4)))*)(kargs() + 8 * 21); }
; DEVI unsigned char* WSP() { return *(unsigned char* const __attribute__((address_space(4)))*)(kargs() + 8 * 22); }
; DEVI void thin_rows(int wv, int l) {
;     const int tid = TID(), lane = tid & 63, wave = __builtin_amdgcn_readfirstlane(tid >> 6);
;     const int gw = BID() * 8 + wave, NGW = GDIM() * 8;
;     unsigned char* ws = WSP(); float* out = OUTP();
;     const float* gkva = IN(8) + l * 256;
;     const float* sp = IN(4) + (size_t)l * 32 * 15 * 512;
;     const float* ssq_zkv = (const float*)(ws + O_SSQZ) + (size_t)(5 + l) * MT;
;     const bf16_t* zkv = (const bf16_t*)(ws + O_ZKV); const bf16_t* pp = (const bf16_t*)(ws + O_PP); bf16_t* pooled = (bf16_t*)(ws + O_POOLED);
;     float* ockv_p = out + OUT_CKVP + (size_t)l * MP * 256; float* ockv_s = out + OUT_CKVS + (size_t)l * MS * 256;
;     for (int c = gw; c < MT / 16; c += NGW) {
.LBB0_977:
	v_mbcnt_lo_u32_b32 v2, -1, 0
	v_mbcnt_hi_u32_b32 v2, -1, v2
	v_lshl_or_b32 v2, s33, 6, v2
	s_sub_i32 s11, s95, 32
	s_and_b32 s11, s11, 0xff
	s_cmp_eq_u32 s85, 0x100
	s_cselect_b32 s11, s11, s95
	v_readfirstlane_b32 s2, v2
	s_ashr_i32 s10, s2, 6
	s_lshl_b32 s2, s11, 3
	s_add_i32 s43, s2, s10
	s_mov_b32 s26, s85
	s_mov_b64 s[4:5], s[0:1]
	s_mov_b64 s[6:7], s[0:1]
	s_mov_b64 s[8:9], s[0:1]
	s_mov_b64 s[2:3], s[0:1]
	s_cmpk_gt_i32 s43, 0x81f
	s_mov_b32 s47, s13
	s_cbranch_scc1 .LBB0_1230
	s_load_dwordx2 s[4:5], s[4:5], 0xb0
	s_nop 0
	s_load_dwordx2 s[6:7], s[6:7], 0xa8
	s_nop 0
	s_load_dwordx2 s[8:9], s[8:9], 0x40
	s_mul_i32 s12, s46, 0x8200
	s_lshl_b32 s49, s26, 3
	s_lshl_b64 s[50:51], s[12:13], 2
	s_waitcnt lgkmcnt(0)
	s_add_u32 s12, s4, s50
	s_addc_u32 s15, s5, s51
	s_add_u32 s48, s12, 0x147800
	s_addc_u32 s42, s15, 0
	s_lshl_b64 s[50:51], s[46:47], 25
	s_add_u32 s12, s6, s50
	s_addc_u32 s15, s7, s51
	s_add_u32 s38, s12, 0x8200000
	s_addc_u32 s96, s15, 0
	s_lshl_b64 s[50:51], s[46:47], 19
	s_load_dwordx2 s[2:3], s[2:3], 0x20
	s_add_u32 s6, s6, s50
	s_addc_u32 s7, s7, s51
	s_add_u32 s36, s6, 0xca78000
	s_addc_u32 s15, s7, 0
	s_mul_i32 s6, s46, 0xf0000
	s_waitcnt lgkmcnt(0)
	s_add_u32 s2, s2, s6
	s_addc_u32 s3, s3, 0
	s_lshl_b32 s12, s46, 8
	s_lshl_b64 s[6:7], s[12:13], 2
	v_and_b32_e32 v5, 63, v2
	s_add_u32 s6, s8, s6
	v_lshlrev_b32_e32 v0, 3, v5
	s_addc_u32 s7, s9, s7
	v_lshl_add_u64 v[6:7], s[4:5], 0, v[0:1]
	s_mov_b64 s[8:9], 0x11510800
	v_lshlrev_b32_e32 v0, 4, v5
	v_lshl_add_u64 v[150:151], v[6:7], 0, s[8:9]
	v_lshl_add_u64 v[152:153], s[6:7], 0, v[0:1]
	v_bfe_u32 v170, v2, 4, 2
	v_lshl_add_u64 v[2:3], s[4:5], 0, v[0:1]
	v_lshlrev_b32_e32 v0, 5, v5
	s_lshl_b32 s8, s11, 7
	s_lshl_b32 s9, s10, 4
	s_mov_b64 s[52:53], 0x12550800
	v_lshlrev_b32_e32 v4, 2, v5
	s_mov_b64 s[6:7], 0x3ce90800
	v_lshl_add_u64 v[158:159], s[2:3], 0, v[0:1]
	s_mov_b64 s[2:3], 0x1c7d0800
	s_add_i32 s8, s8, s9
	s_movk_i32 s30, 0x1000
	v_lshl_add_u64 v[154:155], v[6:7], 0, s[6:7]
	v_lshrrev_b32_e32 v6, 4, v5
	v_lshlrev_b32_e32 v6, 12, v6
	v_bfe_u32 v7, v5, 1, 2
	v_lshl_or_b32 v6, v7, 10, v6
	v_bfe_u32 v7, v5, 3, 1
	v_lshl_or_b32 v6, v7, 8, v6
	v_and_b32_e32 v7, 1, v5
	v_lshl_or_b32 v6, v7, 3, v6
	v_mov_b32_e32 v7, 0
	v_lshl_add_u64 v[6:7], s[4:5], 0, v[6:7]
	v_lshl_add_u64 v[154:155], v[6:7], 0, s[6:7]
	v_lshlrev_b32_e64 v171, v170, 2
	v_lshl_add_u64 v[156:157], v[2:3], 0, s[52:53]
	v_lshl_add_u64 v[160:161], v[2:3], 0, s[2:3]
	v_cmp_lt_u32_e64 s[2:3], 15, v5
	v_cmp_lt_u32_e64 s[4:5], 31, v5
	v_cmp_eq_u32_e64 s[6:7], 3, v170
	s_add_i32 s12, s8, 0xffff8000
	s_lshl_b32 s26, s26, 7
	v_lshlrev_b32_e32 v0, 2, v4
	s_branch .LBB0_981

; DEVI const float* IN(int i) { return *(const float* const __attribute__((address_space(4)))*)(kargs() + 8 * i); }
; DEVI void prologue(int wv, LAS unsigned char* lds) {
;     ...
;     for (int it = gw; it < 2 * I_L; it += NGW) {
;         const int l = it / I_L; int r = it % I_L;
;         unsigned char* wl = ws + O_W + (size_t)l * W_LAYER;
;         if (r < I_IN) { const int kb = r / 101, nb = r % 101, n0 = nb * 32;
;             const int d0 = n0 < 384 ? n0 : n0 < 640 ? 512 + (n0 - 384) : n0 < 672 ? 384 + (n0 - 640) : n0 < 1184 ? 768 + (n0 - 672) : n0 < 2208 ? 1280 + (n0 - 1184) : 2304 + (n0 - 2208);
;             tr_item(IN(6) + (size_t)l * 1024 * 3232, 3232, 1024, IN(5) + l * 1024, (bf16_t*)(wl + W_IN), d0, scr, kb * 64, n0, lane); continue; }
;         r -= I_IN;
;         if (r < I_UQ) { const int kb = r / 24, nb = r % 24, n0 = nb * 32, hd = n0 / 96, dim0 = n0 % 96;
;             const int d0 = dim0 < 64 ? 256 * (hd >> 2) + 128 * (dim0 >> 5) + 32 * (hd & 3) : 512 + 128 * (hd >> 2) + 32 * (hd & 3);
;             tr_item(IN(9) + (size_t)l * 384 * 768, 768, 384, IN(7) + l * 384, (bf16_t*)(wl + W_UQ), d0, scr, kb * 64, n0, lane); continue; }
;         r -= I_UQ;
;         if (r < 2 * I_KV) { const int fold = r < I_KV; if (!fold) r -= I_KV;
;             const int kb = r / 32, nb = r % 32, n0 = nb * 32, hd = n0 / 128, dim0 = n0 % 128;
;             const bool isk = dim0 < 64;
;             const int d0 = isk ? 256 * (hd >> 2) + 128 * (dim0 >> 5) + 32 * (hd & 3) : hd * 64 + (dim0 - 64);
;             bf16_t* dst = (bf16_t*)(wl + (fold ? (isk ? W_K : W_V) : (isk ? W_KC : W_VC)));
;             tr_item(IN(10) + (size_t)l * 256 * 1024, 1024, 256, fold ? IN(8) + l * 256 : nullptr, dst, d0, scr, kb * 64, n0, lane); continue; }
;         r -= 2 * I_KV;
;         if (r < I_A) { tr_item(IN(13) + (size_t)l * 512 * 1024, 1024, 512, nullptr, (bf16_t*)(wl + W_A), (r % 32) * 32, scr, (r / 32) * 64, (r % 32) * 32, lane); continue; }
;         r -= I_A;
;         if (r < I_O) { tr_item(IN(17) + (size_t)l * 1024 * 1024, 1024, 1024, nullptr, (bf16_t*)(wl + W_O), (r % 32) * 32, scr, (r / 32) * 64, (r % 32) * 32, lane); continue; }
;         r -= I_O;
;         if (r < I_UP) { tr_item(IN(19) + (size_t)l * 1024 * 4096, 4096, 1024, IN(18) + l * 1024, (bf16_t*)(wl + W_UP), (r % 128) * 32, scr, (r / 128) * 64, (r % 128) * 32, lane); continue; }
;         r -= I_UP;
.LBB0_1230:
	s_waitcnt vmcnt(0) lgkmcnt(0)
	s_load_dword vcc_lo, s[0:1], 0xb8
	v_readlane_b32 vcc_hi, v255, 5
	s_waitcnt lgkmcnt(0)
	s_cmp_lg_u32 vcc_lo, 0x100
	s_cbranch_scc1 .Lsj_skip2
	s_sub_i32 vcc_hi, vcc_hi, 36
	s_and_b32 vcc_hi, vcc_hi, 0xff
	s_cmp_ge_u32 vcc_hi, 118
	s_cbranch_scc1 .Lsj_skip2
	v_readlane_b32 vcc_lo, v255, 0
	v_writelane_b32 v201, s0, 0
	v_writelane_b32 v201, s1, 1
	v_writelane_b32 v201, s2, 2
	v_writelane_b32 v201, s3, 3
	v_writelane_b32 v201, s4, 4
	v_writelane_b32 v201, s5, 5
	v_writelane_b32 v201, s6, 6
	v_writelane_b32 v201, s7, 7
	v_writelane_b32 v201, s8, 8
	v_writelane_b32 v201, s9, 9
	v_writelane_b32 v201, s10, 10
	v_writelane_b32 v201, s11, 11
	v_writelane_b32 v201, s12, 12
	v_writelane_b32 v201, s13, 13
	v_writelane_b32 v201, s14, 14
	v_writelane_b32 v201, s15, 15
	v_writelane_b32 v201, s16, 16
	v_writelane_b32 v201, s17, 17
	v_writelane_b32 v201, s18, 18
	v_writelane_b32 v201, s19, 19
	v_writelane_b32 v201, s20, 20
	v_writelane_b32 v201, s21, 21
	v_writelane_b32 v201, s22, 22
	v_writelane_b32 v201, s23, 23
	v_writelane_b32 v201, s24, 24
	v_writelane_b32 v201, s25, 25
	v_writelane_b32 v201, s26, 26
	v_writelane_b32 v201, s27, 27
	v_writelane_b32 v201, s28, 28
	v_writelane_b32 v201, s29, 29
	v_writelane_b32 v201, s30, 30
	v_writelane_b32 v201, s31, 31
	v_writelane_b32 v201, s32, 32
	v_writelane_b32 v201, s33, 33
	v_writelane_b32 v201, s34, 34
	v_writelane_b32 v201, s35, 35
	v_writelane_b32 v201, s36, 36
	v_writelane_b32 v201, s37, 37
	v_writelane_b32 v201, s38, 38
	v_writelane_b32 v201, s39, 39
	v_writelane_b32 v201, s40, 40
	v_writelane_b32 v201, s41, 41
	v_writelane_b32 v201, s42, 42
	v_writelane_b32 v201, s43, 43
	v_writelane_b32 v201, s44, 44
	v_writelane_b32 v201, s45, 45
	v_writelane_b32 v201, s46, 46
	v_writelane_b32 v201, s47, 47
	v_writelane_b32 v201, s48, 48
	v_writelane_b32 v201, s49, 49
	v_writelane_b32 v201, s50, 50
	v_writelane_b32 v201, s51, 51
	v_writelane_b32 v201, s52, 52
	v_writelane_b32 v201, s53, 53
	v_writelane_b32 v201, s54, 54
	v_writelane_b32 v201, s55, 55
	v_writelane_b32 v201, s56, 56
	v_writelane_b32 v201, s57, 57
	v_writelane_b32 v201, s58, 58
	v_writelane_b32 v201, s59, 59
	v_writelane_b32 v201, s60, 60
	v_writelane_b32 v201, s61, 61
	v_writelane_b32 v201, s62, 62
	v_writelane_b32 v201, s63, 63
	v_writelane_b32 v202, s64, 0
	v_writelane_b32 v202, s65, 1
	v_writelane_b32 v202, s66, 2
	v_writelane_b32 v202, s67, 3
	v_writelane_b32 v202, s68, 4
	v_writelane_b32 v202, s69, 5
	v_writelane_b32 v202, s70, 6
	v_writelane_b32 v202, s71, 7
	v_writelane_b32 v202, s72, 8
	v_writelane_b32 v202, s73, 9
	v_writelane_b32 v202, s74, 10
	v_writelane_b32 v202, s75, 11
	v_writelane_b32 v202, s76, 12
	v_writelane_b32 v202, s77, 13
	v_writelane_b32 v202, s78, 14
	v_writelane_b32 v202, s79, 15
	v_writelane_b32 v202, s80, 16
	v_writelane_b32 v202, s81, 17
	v_writelane_b32 v202, s82, 18
	v_writelane_b32 v202, s83, 19
	v_writelane_b32 v202, s84, 20
	v_writelane_b32 v202, s85, 21
	v_writelane_b32 v202, s86, 22
	v_writelane_b32 v202, s87, 23
	v_writelane_b32 v202, s88, 24
	v_writelane_b32 v202, s89, 25
	v_writelane_b32 v202, s90, 26
	v_writelane_b32 v202, s91, 27
	v_writelane_b32 v202, s92, 28
	v_writelane_b32 v202, s93, 29
	v_writelane_b32 v202, s94, 30
	v_writelane_b32 v202, s95, 31
	v_writelane_b32 v202, s96, 32
	v_writelane_b32 v202, s97, 33
	v_writelane_b32 v202, s98, 34
	v_writelane_b32 v202, s99, 35
	v_mov_b32_e32 v200, v1
	s_mov_b32 s54, 9664
	s_mov_b32 s52, 10607
	s_cmp_lg_u32 vcc_lo, 0
	s_cbranch_scc0 .Lsj_par2
	s_mov_b32 s54, 3600
	s_mov_b32 s52, 4543
.Lsj_par2:
	s_cmp_gt_i32 s54, s52
	s_cbranch_scc1 .Lsj_ret2
	s_mov_b32 s16, 118
	s_mov_b32 s18, vcc_hi
	s_mov_b32 s53, 2
	s_mov_b64 s[6:7], s[0:1]

; DEVI const float* IN(int i) { return *(const float* const __attribute__((address_space(4)))*)(kargs() + 8 * i); }
; DEVI void prologue(int wv, LAS unsigned char* lds) {
;     ...
;     for (int it = gw; it < 2 * I_L; it += NGW) {
;         const int l = it / I_L; int r = it % I_L;
;         unsigned char* wl = ws + O_W + (size_t)l * W_LAYER;
;         if (r < I_IN) { const int kb = r / 101, nb = r % 101, n0 = nb * 32;
;             const int d0 = n0 < 384 ? n0 : n0 < 640 ? 512 + (n0 - 384) : n0 < 672 ? 384 + (n0 - 640) : n0 < 1184 ? 768 + (n0 - 672) : n0 < 2208 ? 1280 + (n0 - 1184) : 2304 + (n0 - 2208);
;             tr_item(IN(6) + (size_t)l * 1024 * 3232, 3232, 1024, IN(5) + l * 1024, (bf16_t*)(wl + W_IN), d0, scr, kb * 64, n0, lane); continue; }
;         r -= I_IN;
;         if (r < I_UQ) { const int kb = r / 24, nb = r % 24, n0 = nb * 32, hd = n0 / 96, dim0 = n0 % 96;
;             const int d0 = dim0 < 64 ? 256 * (hd >> 2) + 128 * (dim0 >> 5) + 32 * (hd & 3) : 512 + 128 * (hd >> 2) + 32 * (hd & 3);
;             tr_item(IN(9) + (size_t)l * 384 * 768, 768, 384, IN(7) + l * 384, (bf16_t*)(wl + W_UQ), d0, scr, kb * 64, n0, lane); continue; }
;         r -= I_UQ;
;         if (r < 2 * I_KV) { const int fold = r < I_KV; if (!fold) r -= I_KV;
;             const int kb = r / 32, nb = r % 32, n0 = nb * 32, hd = n0 / 128, dim0 = n0 % 128;
;             const bool isk = dim0 < 64;
;             const int d0 = isk ? 256 * (hd >> 2) + 128 * (dim0 >> 5) + 32 * (hd & 3) : hd * 64 + (dim0 - 64);
;             bf16_t* dst = (bf16_t*)(wl + (fold ? (isk ? W_K : W_V) : (isk ? W_KC : W_VC)));
;             tr_item(IN(10) + (size_t)l * 256 * 1024, 1024, 256, fold ? IN(8) + l * 256 : nullptr, dst, d0, scr, kb * 64, n0, lane); continue; }
;         r -= 2 * I_KV;
;         if (r < I_A) { tr_item(IN(13) + (size_t)l * 512 * 1024, 1024, 512, nullptr, (bf16_t*)(wl + W_A), (r % 32) * 32, scr, (r / 32) * 64, (r % 32) * 32, lane); continue; }
;         r -= I_A;
;         if (r < I_O) { tr_item(IN(17) + (size_t)l * 1024 * 1024, 1024, 1024, nullptr, (bf16_t*)(wl + W_O), (r % 32) * 32, scr, (r / 32) * 64, (r % 32) * 32, lane); continue; }
;         r -= I_O;
;         if (r < I_UP) { tr_item(IN(19) + (size_t)l * 1024 * 4096, 4096, 1024, IN(18) + l * 1024, (bf16_t*)(wl + W_UP), (r % 128) * 32, scr, (r / 128) * 64, (r % 128) * 32, lane); continue; }
;         r -= I_UP;
.LBB0_1468:
	s_waitcnt vmcnt(0) lgkmcnt(0)
	s_load_dword vcc_lo, s[0:1], 0xb8
	v_readlane_b32 vcc_hi, v255, 5
	s_waitcnt lgkmcnt(0)
	s_cmp_lg_u32 vcc_lo, 0x100
	s_cbranch_scc1 .Lsj_skip4
	s_sub_i32 vcc_hi, vcc_hi, 48
	s_and_b32 vcc_hi, vcc_hi, 0xff
	s_cmp_ge_u32 vcc_hi, 248
	s_cbranch_scc1 .Lsj_skip4
	v_readlane_b32 vcc_lo, v255, 0
	v_writelane_b32 v201, s0, 0
	v_writelane_b32 v201, s1, 1
	v_writelane_b32 v201, s2, 2
	v_writelane_b32 v201, s3, 3
	v_writelane_b32 v201, s4, 4
	v_writelane_b32 v201, s5, 5
	v_writelane_b32 v201, s6, 6
	v_writelane_b32 v201, s7, 7
	v_writelane_b32 v201, s8, 8
	v_writelane_b32 v201, s9, 9
	v_writelane_b32 v201, s10, 10
	v_writelane_b32 v201, s11, 11
	v_writelane_b32 v201, s12, 12
	v_writelane_b32 v201, s13, 13
	v_writelane_b32 v201, s14, 14
	v_writelane_b32 v201, s15, 15
	v_writelane_b32 v201, s16, 16
	v_writelane_b32 v201, s17, 17
	v_writelane_b32 v201, s18, 18
	v_writelane_b32 v201, s19, 19
	v_writelane_b32 v201, s20, 20
	v_writelane_b32 v201, s21, 21
	v_writelane_b32 v201, s22, 22
	v_writelane_b32 v201, s23, 23
	v_writelane_b32 v201, s24, 24
	v_writelane_b32 v201, s25, 25
	v_writelane_b32 v201, s26, 26
	v_writelane_b32 v201, s27, 27
	v_writelane_b32 v201, s28, 28
	v_writelane_b32 v201, s29, 29
	v_writelane_b32 v201, s30, 30
	v_writelane_b32 v201, s31, 31
	v_writelane_b32 v201, s32, 32
	v_writelane_b32 v201, s33, 33
	v_writelane_b32 v201, s34, 34
	v_writelane_b32 v201, s35, 35
	v_writelane_b32 v201, s36, 36
	v_writelane_b32 v201, s37, 37
	v_writelane_b32 v201, s38, 38
	v_writelane_b32 v201, s39, 39
	v_writelane_b32 v201, s40, 40
	v_writelane_b32 v201, s41, 41
	v_writelane_b32 v201, s42, 42
	v_writelane_b32 v201, s43, 43
	v_writelane_b32 v201, s44, 44
	v_writelane_b32 v201, s45, 45
	v_writelane_b32 v201, s46, 46
	v_writelane_b32 v201, s47, 47
	v_writelane_b32 v201, s48, 48
	v_writelane_b32 v201, s49, 49
	v_writelane_b32 v201, s50, 50
	v_writelane_b32 v201, s51, 51
	v_writelane_b32 v201, s52, 52
	v_writelane_b32 v201, s53, 53
	v_writelane_b32 v201, s54, 54
	v_writelane_b32 v201, s55, 55
	v_writelane_b32 v201, s56, 56
	v_writelane_b32 v201, s57, 57
	v_writelane_b32 v201, s58, 58
	v_writelane_b32 v201, s59, 59
	v_writelane_b32 v201, s60, 60
	v_writelane_b32 v201, s61, 61
	v_writelane_b32 v201, s62, 62
	v_writelane_b32 v201, s63, 63
	v_writelane_b32 v202, s64, 0
	v_writelane_b32 v202, s65, 1
	v_writelane_b32 v202, s66, 2
	v_writelane_b32 v202, s67, 3
	v_writelane_b32 v202, s68, 4
	v_writelane_b32 v202, s69, 5
	v_writelane_b32 v202, s70, 6
	v_writelane_b32 v202, s71, 7
	v_writelane_b32 v202, s72, 8
	v_writelane_b32 v202, s73, 9
	v_writelane_b32 v202, s74, 10
	v_writelane_b32 v202, s75, 11
	v_writelane_b32 v202, s76, 12
	v_writelane_b32 v202, s77, 13
	v_writelane_b32 v202, s78, 14
	v_writelane_b32 v202, s79, 15
	v_writelane_b32 v202, s80, 16
	v_writelane_b32 v202, s81, 17
	v_writelane_b32 v202, s82, 18
	v_writelane_b32 v202, s83, 19
	v_writelane_b32 v202, s84, 20
	v_writelane_b32 v202, s85, 21
	v_writelane_b32 v202, s86, 22
	v_writelane_b32 v202, s87, 23
	v_writelane_b32 v202, s88, 24
	v_writelane_b32 v202, s89, 25
	v_writelane_b32 v202, s90, 26
	v_writelane_b32 v202, s91, 27
	v_writelane_b32 v202, s92, 28
	v_writelane_b32 v202, s93, 29
	v_writelane_b32 v202, s94, 30
	v_writelane_b32 v202, s95, 31
	v_writelane_b32 v202, s96, 32
	v_writelane_b32 v202, s97, 33
	v_writelane_b32 v202, s98, 34
	v_writelane_b32 v202, s99, 35
	v_mov_b32_e32 v200, v1
	s_mov_b32 s54, 10608
	s_mov_b32 s52, 12591
	s_cmp_lg_u32 vcc_lo, 0
	s_cbranch_scc0 .Lsj_par4
	s_mov_b32 s54, 4544
	s_mov_b32 s52, 6527

; DEVI const float* IN(int i) { return *(const float* const __attribute__((address_space(4)))*)(kargs() + 8 * i); }
; DEVI void prologue(int wv, LAS unsigned char* lds) {
;     ...
;     for (int it = gw; it < 2 * I_L; it += NGW) {
;         const int l = it / I_L; int r = it % I_L;
;         unsigned char* wl = ws + O_W + (size_t)l * W_LAYER;
;         if (r < I_IN) { const int kb = r / 101, nb = r % 101, n0 = nb * 32;
;             const int d0 = n0 < 384 ? n0 : n0 < 640 ? 512 + (n0 - 384) : n0 < 672 ? 384 + (n0 - 640) : n0 < 1184 ? 768 + (n0 - 672) : n0 < 2208 ? 1280 + (n0 - 1184) : 2304 + (n0 - 2208);
;             tr_item(IN(6) + (size_t)l * 1024 * 3232, 3232, 1024, IN(5) + l * 1024, (bf16_t*)(wl + W_IN), d0, scr, kb * 64, n0, lane); continue; }
;         r -= I_IN;
;         if (r < I_UQ) { const int kb = r / 24, nb = r % 24, n0 = nb * 32, hd = n0 / 96, dim0 = n0 % 96;
;             const int d0 = dim0 < 64 ? 256 * (hd >> 2) + 128 * (dim0 >> 5) + 32 * (hd & 3) : 512 + 128 * (hd >> 2) + 32 * (hd & 3);
;             tr_item(IN(9) + (size_t)l * 384 * 768, 768, 384, IN(7) + l * 384, (bf16_t*)(wl + W_UQ), d0, scr, kb * 64, n0, lane); continue; }
;         r -= I_UQ;
;         if (r < 2 * I_KV) { const int fold = r < I_KV; if (!fold) r -= I_KV;
;             const int kb = r / 32, nb = r % 32, n0 = nb * 32, hd = n0 / 128, dim0 = n0 % 128;
;             const bool isk = dim0 < 64;
;             const int d0 = isk ? 256 * (hd >> 2) + 128 * (dim0 >> 5) + 32 * (hd & 3) : hd * 64 + (dim0 - 64);
;             bf16_t* dst = (bf16_t*)(wl + (fold ? (isk ? W_K : W_V) : (isk ? W_KC : W_VC)));
;             tr_item(IN(10) + (size_t)l * 256 * 1024, 1024, 256, fold ? IN(8) + l * 256 : nullptr, dst, d0, scr, kb * 64, n0, lane); continue; }
;         r -= 2 * I_KV;
;         if (r < I_A) { tr_item(IN(13) + (size_t)l * 512 * 1024, 1024, 512, nullptr, (bf16_t*)(wl + W_A), (r % 32) * 32, scr, (r / 32) * 64, (r % 32) * 32, lane); continue; }
;         r -= I_A;
;         if (r < I_O) { tr_item(IN(17) + (size_t)l * 1024 * 1024, 1024, 1024, nullptr, (bf16_t*)(wl + W_O), (r % 32) * 32, scr, (r / 32) * 64, (r % 32) * 32, lane); continue; }
;         r -= I_O;
;         if (r < I_UP) { tr_item(IN(19) + (size_t)l * 1024 * 4096, 4096, 1024, IN(18) + l * 1024, (bf16_t*)(wl + W_UP), (r % 128) * 32, scr, (r / 128) * 64, (r % 128) * 32, lane); continue; }
;         r -= I_UP;
.LBB0_1559:
	s_waitcnt vmcnt(0) lgkmcnt(0)
	s_load_dword vcc_lo, s[0:1], 0xb8
	v_readlane_b32 vcc_hi, v255, 5
	s_waitcnt lgkmcnt(0)
	s_cmp_lg_u32 vcc_lo, 0x100
	s_cbranch_scc1 .Lsj_skip5
	s_sub_i32 vcc_hi, vcc_hi, 56
	s_and_b32 vcc_hi, vcc_hi, 0xff
	s_cmp_ge_u32 vcc_hi, 248
	s_cbranch_scc1 .Lsj_skip5
	v_readlane_b32 vcc_lo, v255, 0
	v_writelane_b32 v201, s0, 0
	v_writelane_b32 v201, s1, 1
	v_writelane_b32 v201, s2, 2
	v_writelane_b32 v201, s3, 3
	v_writelane_b32 v201, s4, 4
	v_writelane_b32 v201, s5, 5
	v_writelane_b32 v201, s6, 6
	v_writelane_b32 v201, s7, 7
	v_writelane_b32 v201, s8, 8
	v_writelane_b32 v201, s9, 9
	v_writelane_b32 v201, s10, 10
	v_writelane_b32 v201, s11, 11
	v_writelane_b32 v201, s12, 12
	v_writelane_b32 v201, s13, 13
	v_writelane_b32 v201, s14, 14
	v_writelane_b32 v201, s15, 15
	v_writelane_b32 v201, s16, 16
	v_writelane_b32 v201, s17, 17
	v_writelane_b32 v201, s18, 18
	v_writelane_b32 v201, s19, 19
	v_writelane_b32 v201, s20, 20
	v_writelane_b32 v201, s21, 21
	v_writelane_b32 v201, s22, 22
	v_writelane_b32 v201, s23, 23
	v_writelane_b32 v201, s24, 24
	v_writelane_b32 v201, s25, 25
	v_writelane_b32 v201, s26, 26
	v_writelane_b32 v201, s27, 27
	v_writelane_b32 v201, s28, 28
	v_writelane_b32 v201, s29, 29
	v_writelane_b32 v201, s30, 30
	v_writelane_b32 v201, s31, 31
	v_writelane_b32 v201, s32, 32
	v_writelane_b32 v201, s33, 33
	v_writelane_b32 v201, s34, 34
	v_writelane_b32 v201, s35, 35
	v_writelane_b32 v201, s36, 36
	v_writelane_b32 v201, s37, 37
	v_writelane_b32 v201, s38, 38
	v_writelane_b32 v201, s39, 39
	v_writelane_b32 v201, s40, 40
	v_writelane_b32 v201, s41, 41
	v_writelane_b32 v201, s42, 42
	v_writelane_b32 v201, s43, 43
	v_writelane_b32 v201, s44, 44
	v_writelane_b32 v201, s45, 45
	v_writelane_b32 v201, s46, 46
	v_writelane_b32 v201, s47, 47
	v_writelane_b32 v201, s48, 48
	v_writelane_b32 v201, s49, 49
	v_writelane_b32 v201, s50, 50
	v_writelane_b32 v201, s51, 51
	v_writelane_b32 v201, s52, 52
	v_writelane_b32 v201, s53, 53
	v_writelane_b32 v201, s54, 54
	v_writelane_b32 v201, s55, 55
	v_writelane_b32 v201, s56, 56
	v_writelane_b32 v201, s57, 57
	v_writelane_b32 v201, s58, 58
	v_writelane_b32 v201, s59, 59
	v_writelane_b32 v201, s60, 60
	v_writelane_b32 v201, s61, 61
	v_writelane_b32 v201, s62, 62
	v_writelane_b32 v201, s63, 63
	v_writelane_b32 v202, s64, 0
	v_writelane_b32 v202, s65, 1
	v_writelane_b32 v202, s66, 2
	v_writelane_b32 v202, s67, 3
	v_writelane_b32 v202, s68, 4
	v_writelane_b32 v202, s69, 5
	v_writelane_b32 v202, s70, 6
	v_writelane_b32 v202, s71, 7
	v_writelane_b32 v202, s72, 8
	v_writelane_b32 v202, s73, 9
	v_writelane_b32 v202, s74, 10
	v_writelane_b32 v202, s75, 11
	v_writelane_b32 v202, s76, 12
	v_writelane_b32 v202, s77, 13
	v_writelane_b32 v202, s78, 14
	v_writelane_b32 v202, s79, 15
	v_writelane_b32 v202, s80, 16
	v_writelane_b32 v202, s81, 17
	v_writelane_b32 v202, s82, 18
	v_writelane_b32 v202, s83, 19
	v_writelane_b32 v202, s84, 20
	v_writelane_b32 v202, s85, 21
	v_writelane_b32 v202, s86, 22
	v_writelane_b32 v202, s87, 23
	v_writelane_b32 v202, s88, 24
	v_writelane_b32 v202, s89, 25
	v_writelane_b32 v202, s90, 26
	v_writelane_b32 v202, s91, 27
	v_writelane_b32 v202, s92, 28
	v_writelane_b32 v202, s93, 29
	v_writelane_b32 v202, s94, 30
	v_writelane_b32 v202, s95, 31
	v_writelane_b32 v202, s96, 32
	v_writelane_b32 v202, s97, 33
	v_writelane_b32 v202, s98, 34
	v_writelane_b32 v202, s99, 35
	v_mov_b32_e32 v200, v1
	s_mov_b32 s54, 12592
	s_mov_b32 s52, 13759
	s_cmp_lg_u32 vcc_lo, 0
	s_cbranch_scc0 .Lsj_par5
	s_mov_b32 s54, 6528
	s_mov_b32 s52, 9663
